# FFN K-loops: in every load segment the ds_read_b128 fragment reads are issued first after the barrier, the SALU address arithmetic for the LDS-DMA afterwards (same instructions, same bytes)
# speedup vs baseline: 1.0072x; 1.0072x over previous
.LBB0_182:
	ds_read_b128 v[144:147], v153 offset:0
	ds_read_b128 v[156:159], v153 offset:1024
	ds_read_b128 v[160:163], v153 offset:2048
	ds_read_b128 v[164:167], v153 offset:3072
	ds_read_b128 v[168:171], v154 offset:0
	ds_read_b128 v[172:175], v154 offset:1024
	ds_read_b128 v[176:179], v154 offset:2048
	ds_read_b128 v[180:183], v154 offset:3072
	ds_read_b128 v[184:187], v155 offset:0
	ds_read_b128 v[188:191], v155 offset:1024
	ds_read_b128 v[192:195], v155 offset:2048
	ds_read_b128 v[196:199], v155 offset:3072
	ds_read_b128 v[200:203], v155 offset:4096
	ds_read_b128 v[204:207], v155 offset:5120
	ds_read_b128 v[208:211], v155 offset:6144
	ds_read_b128 v[212:215], v155 offset:7168
	s_add_u32 s30, s72, 0xfff00080
	s_addc_u32 s31, s73, -1
	s_cmp_eq_u32 s41, 60
	s_cselect_b32 s31, s13, s31
	s_cselect_b32 s30, s37, s30
	s_cselect_b32 s75, s11, s40
	s_cselect_b32 s74, s38, s39
	s_add_i32 m0, s29, 0xc000
	s_nop 0
	global_load_lds_dwordx4 v136, s[72:73]
	s_add_i32 m0, s29, 0xe000
	s_nop 0
	global_load_lds_dwordx4 v138, s[72:73]
	s_waitcnt vmcnt(8)
	s_waitcnt lgkmcnt(0)
	s_barrier
	v_mfma_f32_16x16x32_bf16 v[124:127], v[144:147], v[184:187], v[124:127]
	v_mfma_f32_16x16x32_bf16 v[120:123], v[160:163], v[184:187], v[120:123]
	v_mfma_f32_16x16x32_bf16 v[108:111], v[144:147], v[192:195], v[108:111]
	v_mfma_f32_16x16x32_bf16 v[104:107], v[160:163], v[192:195], v[104:107]
	v_mfma_f32_16x16x32_bf16 v[92:95], v[144:147], v[200:203], v[92:95]
	v_mfma_f32_16x16x32_bf16 v[88:91], v[160:163], v[200:203], v[88:91]
	v_mfma_f32_16x16x32_bf16 v[76:79], v[144:147], v[208:211], v[76:79]
	v_mfma_f32_16x16x32_bf16 v[72:75], v[160:163], v[208:211], v[72:75]
	v_mfma_f32_16x16x32_bf16 v[124:127], v[156:159], v[188:191], v[124:127]
	v_mfma_f32_16x16x32_bf16 v[120:123], v[164:167], v[188:191], v[120:123]
	v_mfma_f32_16x16x32_bf16 v[108:111], v[156:159], v[196:199], v[108:111]
	v_mfma_f32_16x16x32_bf16 v[104:107], v[164:167], v[196:199], v[104:107]
	v_mfma_f32_16x16x32_bf16 v[92:95], v[156:159], v[204:207], v[92:95]
	v_mfma_f32_16x16x32_bf16 v[88:91], v[164:167], v[204:207], v[88:91]
	v_mfma_f32_16x16x32_bf16 v[76:79], v[156:159], v[212:215], v[76:79]
	v_mfma_f32_16x16x32_bf16 v[72:75], v[164:167], v[212:215], v[72:75]
	v_mfma_f32_16x16x32_bf16 v[116:119], v[168:171], v[184:187], v[116:119]
	v_mfma_f32_16x16x32_bf16 v[112:115], v[176:179], v[184:187], v[112:115]
	v_mfma_f32_16x16x32_bf16 v[100:103], v[168:171], v[192:195], v[100:103]
	v_mfma_f32_16x16x32_bf16 v[96:99], v[176:179], v[192:195], v[96:99]
	v_mfma_f32_16x16x32_bf16 v[84:87], v[168:171], v[200:203], v[84:87]
	v_mfma_f32_16x16x32_bf16 v[80:83], v[176:179], v[200:203], v[80:83]
	v_mfma_f32_16x16x32_bf16 v[68:71], v[168:171], v[208:211], v[68:71]
	v_mfma_f32_16x16x32_bf16 v[64:67], v[176:179], v[208:211], v[64:67]
	v_mfma_f32_16x16x32_bf16 v[116:119], v[172:175], v[188:191], v[116:119]
	v_mfma_f32_16x16x32_bf16 v[112:115], v[180:183], v[188:191], v[112:115]
	v_mfma_f32_16x16x32_bf16 v[100:103], v[172:175], v[196:199], v[100:103]
	v_mfma_f32_16x16x32_bf16 v[96:99], v[180:183], v[196:199], v[96:99]
	v_mfma_f32_16x16x32_bf16 v[84:87], v[172:175], v[204:207], v[84:87]
	v_mfma_f32_16x16x32_bf16 v[80:83], v[180:183], v[204:207], v[80:83]
	v_mfma_f32_16x16x32_bf16 v[68:71], v[172:175], v[212:215], v[68:71]
	v_mfma_f32_16x16x32_bf16 v[64:67], v[180:183], v[212:215], v[64:67]
	s_barrier
	ds_read_b128 v[184:187], v155 offset:16384
	ds_read_b128 v[188:191], v155 offset:17408
	ds_read_b128 v[192:195], v155 offset:18432
	ds_read_b128 v[196:199], v155 offset:19456
	ds_read_b128 v[200:203], v155 offset:20480
	ds_read_b128 v[204:207], v155 offset:21504
	ds_read_b128 v[208:211], v155 offset:22528
	ds_read_b128 v[212:215], v155 offset:23552
	s_add_u32 s42, s74, 0x100000
	s_addc_u32 s43, s75, 0
	s_add_i32 m0, s29, 0x10000
	s_nop 0
	global_load_lds_dwordx4 v130, s[74:75]
	s_add_i32 m0, s29, 0x12000
	s_nop 0
	global_load_lds_dwordx4 v134, s[74:75]
	s_add_i32 m0, s29, 0x14000
	s_nop 0
	global_load_lds_dwordx4 v130, s[42:43]
	s_add_i32 m0, s29, 0x16000
	s_nop 0
	global_load_lds_dwordx4 v134, s[42:43]
	s_add_i32 m0, s29, 0x0
	s_nop 0
	global_load_lds_dwordx4 v128, s[30:31]
	s_add_i32 m0, s29, 0x2000
	s_nop 0
	global_load_lds_dwordx4 v132, s[30:31]
	s_waitcnt vmcnt(8)
	s_waitcnt lgkmcnt(0)
	s_barrier
	v_mfma_f32_16x16x32_bf16 v[60:63], v[144:147], v[184:187], v[60:63]
	v_mfma_f32_16x16x32_bf16 v[56:59], v[160:163], v[184:187], v[56:59]
	v_mfma_f32_16x16x32_bf16 v[44:47], v[144:147], v[192:195], v[44:47]
	v_mfma_f32_16x16x32_bf16 v[40:43], v[160:163], v[192:195], v[40:43]
	v_mfma_f32_16x16x32_bf16 v[28:31], v[144:147], v[200:203], v[28:31]
	v_mfma_f32_16x16x32_bf16 v[24:27], v[160:163], v[200:203], v[24:27]
	v_mfma_f32_16x16x32_bf16 v[12:15], v[144:147], v[208:211], v[12:15]
	v_mfma_f32_16x16x32_bf16 v[8:11], v[160:163], v[208:211], v[8:11]
	v_mfma_f32_16x16x32_bf16 v[60:63], v[156:159], v[188:191], v[60:63]
	v_mfma_f32_16x16x32_bf16 v[56:59], v[164:167], v[188:191], v[56:59]
	v_mfma_f32_16x16x32_bf16 v[44:47], v[156:159], v[196:199], v[44:47]
	v_mfma_f32_16x16x32_bf16 v[40:43], v[164:167], v[196:199], v[40:43]
	v_mfma_f32_16x16x32_bf16 v[28:31], v[156:159], v[204:207], v[28:31]
	v_mfma_f32_16x16x32_bf16 v[24:27], v[164:167], v[204:207], v[24:27]
	v_mfma_f32_16x16x32_bf16 v[12:15], v[156:159], v[212:215], v[12:15]
	v_mfma_f32_16x16x32_bf16 v[8:11], v[164:167], v[212:215], v[8:11]
	v_mfma_f32_16x16x32_bf16 v[52:55], v[168:171], v[184:187], v[52:55]
	v_mfma_f32_16x16x32_bf16 v[48:51], v[176:179], v[184:187], v[48:51]
	v_mfma_f32_16x16x32_bf16 v[36:39], v[168:171], v[192:195], v[36:39]
	v_mfma_f32_16x16x32_bf16 v[32:35], v[176:179], v[192:195], v[32:35]
	v_mfma_f32_16x16x32_bf16 v[20:23], v[168:171], v[200:203], v[20:23]
	v_mfma_f32_16x16x32_bf16 v[16:19], v[176:179], v[200:203], v[16:19]
	v_mfma_f32_16x16x32_bf16 v[4:7], v[168:171], v[208:211], v[4:7]
	v_mfma_f32_16x16x32_bf16 v[0:3], v[176:179], v[208:211], v[0:3]
	v_mfma_f32_16x16x32_bf16 v[52:55], v[172:175], v[188:191], v[52:55]
	v_mfma_f32_16x16x32_bf16 v[48:51], v[180:183], v[188:191], v[48:51]
	v_mfma_f32_16x16x32_bf16 v[36:39], v[172:175], v[196:199], v[36:39]
	v_mfma_f32_16x16x32_bf16 v[32:35], v[180:183], v[196:199], v[32:35]
	v_mfma_f32_16x16x32_bf16 v[20:23], v[172:175], v[204:207], v[20:23]
	v_mfma_f32_16x16x32_bf16 v[16:19], v[180:183], v[204:207], v[16:19]
	v_mfma_f32_16x16x32_bf16 v[4:7], v[172:175], v[212:215], v[4:7]
	v_mfma_f32_16x16x32_bf16 v[0:3], v[180:183], v[212:215], v[0:3]
	s_barrier
	ds_read_b128 v[144:147], v153 offset:32768
	ds_read_b128 v[156:159], v153 offset:33792
	ds_read_b128 v[160:163], v153 offset:34816
	ds_read_b128 v[164:167], v153 offset:35840
	ds_read_b128 v[168:171], v154 offset:32768
	ds_read_b128 v[172:175], v154 offset:33792
	ds_read_b128 v[176:179], v154 offset:34816
	ds_read_b128 v[180:183], v154 offset:35840
	ds_read_b128 v[184:187], v155 offset:32768
	ds_read_b128 v[188:191], v155 offset:33792
	ds_read_b128 v[192:195], v155 offset:34816
	ds_read_b128 v[196:199], v155 offset:35840
	ds_read_b128 v[200:203], v155 offset:36864
	ds_read_b128 v[204:207], v155 offset:37888
	ds_read_b128 v[208:211], v155 offset:38912
	ds_read_b128 v[212:215], v155 offset:39936
	s_add_u32 s98, s30, 0x100000
	s_addc_u32 s99, s31, 0
	s_add_i32 m0, s29, 0x4000
	s_nop 0
	global_load_lds_dwordx4 v128, s[98:99]
	s_add_i32 m0, s29, 0x6000
	s_nop 0
	global_load_lds_dwordx4 v132, s[98:99]
	s_waitcnt vmcnt(8)
	s_waitcnt lgkmcnt(0)
	s_barrier
	v_mfma_f32_16x16x32_bf16 v[124:127], v[144:147], v[184:187], v[124:127]
	v_mfma_f32_16x16x32_bf16 v[120:123], v[160:163], v[184:187], v[120:123]
	v_mfma_f32_16x16x32_bf16 v[108:111], v[144:147], v[192:195], v[108:111]
	v_mfma_f32_16x16x32_bf16 v[104:107], v[160:163], v[192:195], v[104:107]
	v_mfma_f32_16x16x32_bf16 v[92:95], v[144:147], v[200:203], v[92:95]
	v_mfma_f32_16x16x32_bf16 v[88:91], v[160:163], v[200:203], v[88:91]
	v_mfma_f32_16x16x32_bf16 v[76:79], v[144:147], v[208:211], v[76:79]
	v_mfma_f32_16x16x32_bf16 v[72:75], v[160:163], v[208:211], v[72:75]
	v_mfma_f32_16x16x32_bf16 v[124:127], v[156:159], v[188:191], v[124:127]
	v_mfma_f32_16x16x32_bf16 v[120:123], v[164:167], v[188:191], v[120:123]
	v_mfma_f32_16x16x32_bf16 v[108:111], v[156:159], v[196:199], v[108:111]
	v_mfma_f32_16x16x32_bf16 v[104:107], v[164:167], v[196:199], v[104:107]
	v_mfma_f32_16x16x32_bf16 v[92:95], v[156:159], v[204:207], v[92:95]
	v_mfma_f32_16x16x32_bf16 v[88:91], v[164:167], v[204:207], v[88:91]
	v_mfma_f32_16x16x32_bf16 v[76:79], v[156:159], v[212:215], v[76:79]
	v_mfma_f32_16x16x32_bf16 v[72:75], v[164:167], v[212:215], v[72:75]
	v_mfma_f32_16x16x32_bf16 v[116:119], v[168:171], v[184:187], v[116:119]
	v_mfma_f32_16x16x32_bf16 v[112:115], v[176:179], v[184:187], v[112:115]
	v_mfma_f32_16x16x32_bf16 v[100:103], v[168:171], v[192:195], v[100:103]
	v_mfma_f32_16x16x32_bf16 v[96:99], v[176:179], v[192:195], v[96:99]
	v_mfma_f32_16x16x32_bf16 v[84:87], v[168:171], v[200:203], v[84:87]
	v_mfma_f32_16x16x32_bf16 v[80:83], v[176:179], v[200:203], v[80:83]
	v_mfma_f32_16x16x32_bf16 v[68:71], v[168:171], v[208:211], v[68:71]
	v_mfma_f32_16x16x32_bf16 v[64:67], v[176:179], v[208:211], v[64:67]
	v_mfma_f32_16x16x32_bf16 v[116:119], v[172:175], v[188:191], v[116:119]
	v_mfma_f32_16x16x32_bf16 v[112:115], v[180:183], v[188:191], v[112:115]
	v_mfma_f32_16x16x32_bf16 v[100:103], v[172:175], v[196:199], v[100:103]
	v_mfma_f32_16x16x32_bf16 v[96:99], v[180:183], v[196:199], v[96:99]
	v_mfma_f32_16x16x32_bf16 v[84:87], v[172:175], v[204:207], v[84:87]
	v_mfma_f32_16x16x32_bf16 v[80:83], v[180:183], v[204:207], v[80:83]
	v_mfma_f32_16x16x32_bf16 v[68:71], v[172:175], v[212:215], v[68:71]
	v_mfma_f32_16x16x32_bf16 v[64:67], v[180:183], v[212:215], v[64:67]
	s_barrier
	ds_read_b128 v[184:187], v155 offset:49152
	ds_read_b128 v[188:191], v155 offset:50176
	ds_read_b128 v[192:195], v155 offset:51200
	ds_read_b128 v[196:199], v155 offset:52224
	ds_read_b128 v[200:203], v155 offset:53248
	ds_read_b128 v[204:207], v155 offset:54272
	ds_read_b128 v[208:211], v155 offset:55296
	ds_read_b128 v[212:215], v155 offset:56320
	s_add_u32 s100, s74, 0x80
	s_addc_u32 s101, s75, 0
	s_add_u32 s42, s74, 0x100080
	s_addc_u32 s43, s75, 0
	s_add_u32 s98, s30, 0x80
	s_addc_u32 s99, s31, 0
	s_add_i32 m0, s29, 0x18000
	s_nop 0
	global_load_lds_dwordx4 v130, s[100:101]
	s_add_i32 m0, s29, 0x1a000
	s_nop 0
	global_load_lds_dwordx4 v134, s[100:101]
	s_add_i32 m0, s29, 0x1c000
	s_nop 0
	global_load_lds_dwordx4 v130, s[42:43]
	s_add_i32 m0, s29, 0x1e000
	s_nop 0
	global_load_lds_dwordx4 v134, s[42:43]
	s_add_i32 m0, s29, 0x8000
	s_nop 0
	global_load_lds_dwordx4 v128, s[98:99]
	s_add_i32 m0, s29, 0xa000
	s_nop 0
	global_load_lds_dwordx4 v132, s[98:99]
	s_waitcnt vmcnt(8)
	s_waitcnt lgkmcnt(0)
	s_barrier
	v_mfma_f32_16x16x32_bf16 v[60:63], v[144:147], v[184:187], v[60:63]
	v_mfma_f32_16x16x32_bf16 v[56:59], v[160:163], v[184:187], v[56:59]
	v_mfma_f32_16x16x32_bf16 v[44:47], v[144:147], v[192:195], v[44:47]
	v_mfma_f32_16x16x32_bf16 v[40:43], v[160:163], v[192:195], v[40:43]
	v_mfma_f32_16x16x32_bf16 v[28:31], v[144:147], v[200:203], v[28:31]
	v_mfma_f32_16x16x32_bf16 v[24:27], v[160:163], v[200:203], v[24:27]
	v_mfma_f32_16x16x32_bf16 v[12:15], v[144:147], v[208:211], v[12:15]
	v_mfma_f32_16x16x32_bf16 v[8:11], v[160:163], v[208:211], v[8:11]
	v_mfma_f32_16x16x32_bf16 v[60:63], v[156:159], v[188:191], v[60:63]
	v_mfma_f32_16x16x32_bf16 v[56:59], v[164:167], v[188:191], v[56:59]
	v_mfma_f32_16x16x32_bf16 v[44:47], v[156:159], v[196:199], v[44:47]
	v_mfma_f32_16x16x32_bf16 v[40:43], v[164:167], v[196:199], v[40:43]
	v_mfma_f32_16x16x32_bf16 v[28:31], v[156:159], v[204:207], v[28:31]
	v_mfma_f32_16x16x32_bf16 v[24:27], v[164:167], v[204:207], v[24:27]
	v_mfma_f32_16x16x32_bf16 v[12:15], v[156:159], v[212:215], v[12:15]
	v_mfma_f32_16x16x32_bf16 v[8:11], v[164:167], v[212:215], v[8:11]
	v_mfma_f32_16x16x32_bf16 v[52:55], v[168:171], v[184:187], v[52:55]
	v_mfma_f32_16x16x32_bf16 v[48:51], v[176:179], v[184:187], v[48:51]
	v_mfma_f32_16x16x32_bf16 v[36:39], v[168:171], v[192:195], v[36:39]
	v_mfma_f32_16x16x32_bf16 v[32:35], v[176:179], v[192:195], v[32:35]
	v_mfma_f32_16x16x32_bf16 v[20:23], v[168:171], v[200:203], v[20:23]
	v_mfma_f32_16x16x32_bf16 v[16:19], v[176:179], v[200:203], v[16:19]
	v_mfma_f32_16x16x32_bf16 v[4:7], v[168:171], v[208:211], v[4:7]
	v_mfma_f32_16x16x32_bf16 v[0:3], v[176:179], v[208:211], v[0:3]
	v_mfma_f32_16x16x32_bf16 v[52:55], v[172:175], v[188:191], v[52:55]
	v_mfma_f32_16x16x32_bf16 v[48:51], v[180:183], v[188:191], v[48:51]
	v_mfma_f32_16x16x32_bf16 v[36:39], v[172:175], v[196:199], v[36:39]
	v_mfma_f32_16x16x32_bf16 v[32:35], v[180:183], v[196:199], v[32:35]
	v_mfma_f32_16x16x32_bf16 v[20:23], v[172:175], v[204:207], v[20:23]
	v_mfma_f32_16x16x32_bf16 v[16:19], v[180:183], v[204:207], v[16:19]
	v_mfma_f32_16x16x32_bf16 v[4:7], v[172:175], v[212:215], v[4:7]
	v_mfma_f32_16x16x32_bf16 v[0:3], v[180:183], v[212:215], v[0:3]
	s_barrier
	s_add_i32 s41, s41, 2
	s_add_u32 s72, s72, 0x100
	s_addc_u32 s73, s73, 0
	s_add_u32 s39, s39, 0x100
	s_addc_u32 s40, s40, 0
	s_cmp_gt_u32 s41, 61
	s_cbranch_scc0 .LBB0_182
	s_and_b64 vcc, exec, s[6:7]
	s_cbranch_vccz .LBB0_185
	s_barrier

.LBB0_401:
	ds_read_b128 v[142:145], v169 offset:0
	ds_read_b128 v[146:149], v169 offset:1024
	ds_read_b128 v[150:153], v169 offset:2048
	ds_read_b128 v[154:157], v169 offset:3072
	ds_read_b128 v[158:161], v170 offset:0
	ds_read_b128 v[162:165], v170 offset:1024
	ds_read_b128 v[172:175], v170 offset:2048
	ds_read_b128 v[176:179], v170 offset:3072
	ds_read_b128 v[180:183], v171 offset:0
	ds_read_b128 v[184:187], v171 offset:1024
	ds_read_b128 v[188:191], v171 offset:2048
	ds_read_b128 v[192:195], v171 offset:3072
	ds_read_b128 v[196:199], v171 offset:4096
	ds_read_b128 v[200:203], v171 offset:5120
	ds_read_b128 v[204:207], v171 offset:6144
	ds_read_b128 v[208:211], v171 offset:7168
	s_add_i32 s38, s30, 2
	s_add_u32 s46, s44, 0x100
	s_addc_u32 s47, s45, 0
	s_cmp_eq_u32 s17, s30
	s_cselect_b32 s30, s34, s46
	s_cselect_b32 s31, s35, s47
	s_cselect_b32 s53, s41, s37
	s_cselect_b32 s52, s40, s36
	s_add_i32 m0, s60, 0xc000
	s_nop 0
	global_load_lds_dwordx4 v136, s[44:45]
	s_add_i32 m0, s60, 0xe000
	s_nop 0
	global_load_lds_dwordx4 v138, s[44:45]
	s_waitcnt vmcnt(8)
	s_waitcnt lgkmcnt(0)
	s_barrier
	v_mfma_f32_16x16x32_bf16 v[124:127], v[142:145], v[180:183], v[124:127]
	v_mfma_f32_16x16x32_bf16 v[120:123], v[150:153], v[180:183], v[120:123]
	v_mfma_f32_16x16x32_bf16 v[108:111], v[142:145], v[188:191], v[108:111]
	v_mfma_f32_16x16x32_bf16 v[104:107], v[150:153], v[188:191], v[104:107]
	v_mfma_f32_16x16x32_bf16 v[92:95], v[142:145], v[196:199], v[92:95]
	v_mfma_f32_16x16x32_bf16 v[88:91], v[150:153], v[196:199], v[88:91]
	v_mfma_f32_16x16x32_bf16 v[76:79], v[142:145], v[204:207], v[76:79]
	v_mfma_f32_16x16x32_bf16 v[72:75], v[150:153], v[204:207], v[72:75]
	v_mfma_f32_16x16x32_bf16 v[124:127], v[146:149], v[184:187], v[124:127]
	v_mfma_f32_16x16x32_bf16 v[120:123], v[154:157], v[184:187], v[120:123]
	v_mfma_f32_16x16x32_bf16 v[108:111], v[146:149], v[192:195], v[108:111]
	v_mfma_f32_16x16x32_bf16 v[104:107], v[154:157], v[192:195], v[104:107]
	v_mfma_f32_16x16x32_bf16 v[92:95], v[146:149], v[200:203], v[92:95]
	v_mfma_f32_16x16x32_bf16 v[88:91], v[154:157], v[200:203], v[88:91]
	v_mfma_f32_16x16x32_bf16 v[76:79], v[146:149], v[208:211], v[76:79]
	v_mfma_f32_16x16x32_bf16 v[72:75], v[154:157], v[208:211], v[72:75]
	v_mfma_f32_16x16x32_bf16 v[116:119], v[158:161], v[180:183], v[116:119]
	v_mfma_f32_16x16x32_bf16 v[112:115], v[172:175], v[180:183], v[112:115]
	v_mfma_f32_16x16x32_bf16 v[100:103], v[158:161], v[188:191], v[100:103]
	v_mfma_f32_16x16x32_bf16 v[96:99], v[172:175], v[188:191], v[96:99]
	v_mfma_f32_16x16x32_bf16 v[84:87], v[158:161], v[196:199], v[84:87]
	v_mfma_f32_16x16x32_bf16 v[80:83], v[172:175], v[196:199], v[80:83]
	v_mfma_f32_16x16x32_bf16 v[68:71], v[158:161], v[204:207], v[68:71]
	v_mfma_f32_16x16x32_bf16 v[64:67], v[172:175], v[204:207], v[64:67]
	v_mfma_f32_16x16x32_bf16 v[116:119], v[162:165], v[184:187], v[116:119]
	v_mfma_f32_16x16x32_bf16 v[112:115], v[176:179], v[184:187], v[112:115]
	v_mfma_f32_16x16x32_bf16 v[100:103], v[162:165], v[192:195], v[100:103]
	v_mfma_f32_16x16x32_bf16 v[96:99], v[176:179], v[192:195], v[96:99]
	v_mfma_f32_16x16x32_bf16 v[84:87], v[162:165], v[200:203], v[84:87]
	v_mfma_f32_16x16x32_bf16 v[80:83], v[176:179], v[200:203], v[80:83]
	v_mfma_f32_16x16x32_bf16 v[68:71], v[162:165], v[208:211], v[68:71]
	v_mfma_f32_16x16x32_bf16 v[64:67], v[176:179], v[208:211], v[64:67]
	s_barrier
	ds_read_b128 v[180:183], v171 offset:16384
	ds_read_b128 v[184:187], v171 offset:17408
	ds_read_b128 v[188:191], v171 offset:18432
	ds_read_b128 v[192:195], v171 offset:19456
	ds_read_b128 v[196:199], v171 offset:20480
	ds_read_b128 v[200:203], v171 offset:21504
	ds_read_b128 v[204:207], v171 offset:22528
	ds_read_b128 v[208:211], v171 offset:23552
	s_add_u32 s42, s52, 0x2b0000
	s_addc_u32 s43, s53, 0
	s_add_i32 m0, s60, 0x10000
	s_nop 0
	global_load_lds_dwordx4 v130, s[52:53]
	s_add_i32 m0, s60, 0x12000
	s_nop 0
	global_load_lds_dwordx4 v134, s[52:53]
	s_add_i32 m0, s60, 0x14000
	s_nop 0
	global_load_lds_dwordx4 v130, s[42:43]
	s_add_i32 m0, s60, 0x16000
	s_nop 0
	global_load_lds_dwordx4 v134, s[42:43]
	s_add_i32 m0, s60, 0x0
	s_nop 0
	global_load_lds_dwordx4 v128, s[30:31]
	s_add_i32 m0, s60, 0x2000
	s_nop 0
	global_load_lds_dwordx4 v132, s[30:31]
	s_waitcnt vmcnt(8)
	s_waitcnt lgkmcnt(0)
	s_barrier
	v_mfma_f32_16x16x32_bf16 v[60:63], v[142:145], v[180:183], v[60:63]
	v_mfma_f32_16x16x32_bf16 v[56:59], v[150:153], v[180:183], v[56:59]
	v_mfma_f32_16x16x32_bf16 v[44:47], v[142:145], v[188:191], v[44:47]
	v_mfma_f32_16x16x32_bf16 v[40:43], v[150:153], v[188:191], v[40:43]
	v_mfma_f32_16x16x32_bf16 v[28:31], v[142:145], v[196:199], v[28:31]
	v_mfma_f32_16x16x32_bf16 v[24:27], v[150:153], v[196:199], v[24:27]
	v_mfma_f32_16x16x32_bf16 v[12:15], v[142:145], v[204:207], v[12:15]
	v_mfma_f32_16x16x32_bf16 v[8:11], v[150:153], v[204:207], v[8:11]
	v_mfma_f32_16x16x32_bf16 v[60:63], v[146:149], v[184:187], v[60:63]
	v_mfma_f32_16x16x32_bf16 v[56:59], v[154:157], v[184:187], v[56:59]
	v_mfma_f32_16x16x32_bf16 v[44:47], v[146:149], v[192:195], v[44:47]
	v_mfma_f32_16x16x32_bf16 v[40:43], v[154:157], v[192:195], v[40:43]
	v_mfma_f32_16x16x32_bf16 v[28:31], v[146:149], v[200:203], v[28:31]
	v_mfma_f32_16x16x32_bf16 v[24:27], v[154:157], v[200:203], v[24:27]
	v_mfma_f32_16x16x32_bf16 v[12:15], v[146:149], v[208:211], v[12:15]
	v_mfma_f32_16x16x32_bf16 v[8:11], v[154:157], v[208:211], v[8:11]
	v_mfma_f32_16x16x32_bf16 v[52:55], v[158:161], v[180:183], v[52:55]
	v_mfma_f32_16x16x32_bf16 v[48:51], v[172:175], v[180:183], v[48:51]
	v_mfma_f32_16x16x32_bf16 v[36:39], v[158:161], v[188:191], v[36:39]
	v_mfma_f32_16x16x32_bf16 v[32:35], v[172:175], v[188:191], v[32:35]
	v_mfma_f32_16x16x32_bf16 v[20:23], v[158:161], v[196:199], v[20:23]
	v_mfma_f32_16x16x32_bf16 v[16:19], v[172:175], v[196:199], v[16:19]
	v_mfma_f32_16x16x32_bf16 v[4:7], v[158:161], v[204:207], v[4:7]
	v_mfma_f32_16x16x32_bf16 v[0:3], v[172:175], v[204:207], v[0:3]
	v_mfma_f32_16x16x32_bf16 v[52:55], v[162:165], v[184:187], v[52:55]
	v_mfma_f32_16x16x32_bf16 v[48:51], v[176:179], v[184:187], v[48:51]
	v_mfma_f32_16x16x32_bf16 v[36:39], v[162:165], v[192:195], v[36:39]
	v_mfma_f32_16x16x32_bf16 v[32:35], v[176:179], v[192:195], v[32:35]
	v_mfma_f32_16x16x32_bf16 v[20:23], v[162:165], v[200:203], v[20:23]
	v_mfma_f32_16x16x32_bf16 v[16:19], v[176:179], v[200:203], v[16:19]
	v_mfma_f32_16x16x32_bf16 v[4:7], v[162:165], v[208:211], v[4:7]
	v_mfma_f32_16x16x32_bf16 v[0:3], v[176:179], v[208:211], v[0:3]
	s_barrier
	ds_read_b128 v[142:145], v169 offset:32768
	ds_read_b128 v[146:149], v169 offset:33792
	ds_read_b128 v[150:153], v169 offset:34816
	ds_read_b128 v[154:157], v169 offset:35840
	ds_read_b128 v[158:161], v170 offset:32768
	ds_read_b128 v[162:165], v170 offset:33792
	ds_read_b128 v[172:175], v170 offset:34816
	ds_read_b128 v[176:179], v170 offset:35840
	ds_read_b128 v[180:183], v171 offset:32768
	ds_read_b128 v[184:187], v171 offset:33792
	ds_read_b128 v[188:191], v171 offset:34816
	ds_read_b128 v[192:195], v171 offset:35840
	ds_read_b128 v[196:199], v171 offset:36864
	ds_read_b128 v[200:203], v171 offset:37888
	ds_read_b128 v[204:207], v171 offset:38912
	ds_read_b128 v[208:211], v171 offset:39936
	s_add_u32 s98, s30, 0x2b0000
	s_addc_u32 s99, s31, 0
	s_add_i32 m0, s60, 0x4000
	s_nop 0
	global_load_lds_dwordx4 v128, s[98:99]
	s_add_i32 m0, s60, 0x6000
	s_nop 0
	global_load_lds_dwordx4 v132, s[98:99]
	s_waitcnt vmcnt(8)
	s_waitcnt lgkmcnt(0)
	s_barrier
	v_mfma_f32_16x16x32_bf16 v[124:127], v[142:145], v[180:183], v[124:127]
	v_mfma_f32_16x16x32_bf16 v[120:123], v[150:153], v[180:183], v[120:123]
	v_mfma_f32_16x16x32_bf16 v[108:111], v[142:145], v[188:191], v[108:111]
	v_mfma_f32_16x16x32_bf16 v[104:107], v[150:153], v[188:191], v[104:107]
	v_mfma_f32_16x16x32_bf16 v[92:95], v[142:145], v[196:199], v[92:95]
	v_mfma_f32_16x16x32_bf16 v[88:91], v[150:153], v[196:199], v[88:91]
	v_mfma_f32_16x16x32_bf16 v[76:79], v[142:145], v[204:207], v[76:79]
	v_mfma_f32_16x16x32_bf16 v[72:75], v[150:153], v[204:207], v[72:75]
	v_mfma_f32_16x16x32_bf16 v[124:127], v[146:149], v[184:187], v[124:127]
	v_mfma_f32_16x16x32_bf16 v[120:123], v[154:157], v[184:187], v[120:123]
	v_mfma_f32_16x16x32_bf16 v[108:111], v[146:149], v[192:195], v[108:111]
	v_mfma_f32_16x16x32_bf16 v[104:107], v[154:157], v[192:195], v[104:107]
	v_mfma_f32_16x16x32_bf16 v[92:95], v[146:149], v[200:203], v[92:95]
	v_mfma_f32_16x16x32_bf16 v[88:91], v[154:157], v[200:203], v[88:91]
	v_mfma_f32_16x16x32_bf16 v[76:79], v[146:149], v[208:211], v[76:79]
	v_mfma_f32_16x16x32_bf16 v[72:75], v[154:157], v[208:211], v[72:75]
	v_mfma_f32_16x16x32_bf16 v[116:119], v[158:161], v[180:183], v[116:119]
	v_mfma_f32_16x16x32_bf16 v[112:115], v[172:175], v[180:183], v[112:115]
	v_mfma_f32_16x16x32_bf16 v[100:103], v[158:161], v[188:191], v[100:103]
	v_mfma_f32_16x16x32_bf16 v[96:99], v[172:175], v[188:191], v[96:99]
	v_mfma_f32_16x16x32_bf16 v[84:87], v[158:161], v[196:199], v[84:87]
	v_mfma_f32_16x16x32_bf16 v[80:83], v[172:175], v[196:199], v[80:83]
	v_mfma_f32_16x16x32_bf16 v[68:71], v[158:161], v[204:207], v[68:71]
	v_mfma_f32_16x16x32_bf16 v[64:67], v[172:175], v[204:207], v[64:67]
	v_mfma_f32_16x16x32_bf16 v[116:119], v[162:165], v[184:187], v[116:119]
	v_mfma_f32_16x16x32_bf16 v[112:115], v[176:179], v[184:187], v[112:115]
	v_mfma_f32_16x16x32_bf16 v[100:103], v[162:165], v[192:195], v[100:103]
	v_mfma_f32_16x16x32_bf16 v[96:99], v[176:179], v[192:195], v[96:99]
	v_mfma_f32_16x16x32_bf16 v[84:87], v[162:165], v[200:203], v[84:87]
	v_mfma_f32_16x16x32_bf16 v[80:83], v[176:179], v[200:203], v[80:83]
	v_mfma_f32_16x16x32_bf16 v[68:71], v[162:165], v[208:211], v[68:71]
	v_mfma_f32_16x16x32_bf16 v[64:67], v[176:179], v[208:211], v[64:67]
	s_barrier
	ds_read_b128 v[180:183], v171 offset:49152
	ds_read_b128 v[184:187], v171 offset:50176
	ds_read_b128 v[188:191], v171 offset:51200
	ds_read_b128 v[192:195], v171 offset:52224
	ds_read_b128 v[196:199], v171 offset:53248
	ds_read_b128 v[200:203], v171 offset:54272
	ds_read_b128 v[204:207], v171 offset:55296
	ds_read_b128 v[208:211], v171 offset:56320
	s_add_u32 s100, s52, 0x80
	s_addc_u32 s101, s53, 0
	s_add_u32 s42, s52, 0x2b0080
	s_addc_u32 s43, s53, 0
	s_add_u32 s98, s30, 0x80
	s_addc_u32 s99, s31, 0
	s_add_i32 m0, s60, 0x18000
	s_nop 0
	global_load_lds_dwordx4 v130, s[100:101]
	s_add_i32 m0, s60, 0x1a000
	s_nop 0
	global_load_lds_dwordx4 v134, s[100:101]
	s_add_i32 m0, s60, 0x1c000
	s_nop 0
	global_load_lds_dwordx4 v130, s[42:43]
	s_add_i32 m0, s60, 0x1e000
	s_nop 0
	global_load_lds_dwordx4 v134, s[42:43]
	s_add_i32 m0, s60, 0x8000
	s_nop 0
	global_load_lds_dwordx4 v128, s[98:99]
	s_add_i32 m0, s60, 0xa000
	s_nop 0
	global_load_lds_dwordx4 v132, s[98:99]
	s_waitcnt vmcnt(8)
	s_waitcnt lgkmcnt(0)
	s_barrier
	v_mfma_f32_16x16x32_bf16 v[60:63], v[142:145], v[180:183], v[60:63]
	v_mfma_f32_16x16x32_bf16 v[56:59], v[150:153], v[180:183], v[56:59]
	v_mfma_f32_16x16x32_bf16 v[44:47], v[142:145], v[188:191], v[44:47]
	v_mfma_f32_16x16x32_bf16 v[40:43], v[150:153], v[188:191], v[40:43]
	v_mfma_f32_16x16x32_bf16 v[28:31], v[142:145], v[196:199], v[28:31]
	v_mfma_f32_16x16x32_bf16 v[24:27], v[150:153], v[196:199], v[24:27]
	v_mfma_f32_16x16x32_bf16 v[12:15], v[142:145], v[204:207], v[12:15]
	v_mfma_f32_16x16x32_bf16 v[8:11], v[150:153], v[204:207], v[8:11]
	v_mfma_f32_16x16x32_bf16 v[60:63], v[146:149], v[184:187], v[60:63]
	v_mfma_f32_16x16x32_bf16 v[56:59], v[154:157], v[184:187], v[56:59]
	v_mfma_f32_16x16x32_bf16 v[44:47], v[146:149], v[192:195], v[44:47]
	v_mfma_f32_16x16x32_bf16 v[40:43], v[154:157], v[192:195], v[40:43]
	v_mfma_f32_16x16x32_bf16 v[28:31], v[146:149], v[200:203], v[28:31]
	v_mfma_f32_16x16x32_bf16 v[24:27], v[154:157], v[200:203], v[24:27]
	v_mfma_f32_16x16x32_bf16 v[12:15], v[146:149], v[208:211], v[12:15]
	v_mfma_f32_16x16x32_bf16 v[8:11], v[154:157], v[208:211], v[8:11]
	v_mfma_f32_16x16x32_bf16 v[52:55], v[158:161], v[180:183], v[52:55]
	v_mfma_f32_16x16x32_bf16 v[48:51], v[172:175], v[180:183], v[48:51]
	v_mfma_f32_16x16x32_bf16 v[36:39], v[158:161], v[188:191], v[36:39]
	v_mfma_f32_16x16x32_bf16 v[32:35], v[172:175], v[188:191], v[32:35]
	v_mfma_f32_16x16x32_bf16 v[20:23], v[158:161], v[196:199], v[20:23]
	v_mfma_f32_16x16x32_bf16 v[16:19], v[172:175], v[196:199], v[16:19]
	v_mfma_f32_16x16x32_bf16 v[4:7], v[158:161], v[204:207], v[4:7]
	v_mfma_f32_16x16x32_bf16 v[0:3], v[172:175], v[204:207], v[0:3]
	v_mfma_f32_16x16x32_bf16 v[52:55], v[162:165], v[184:187], v[52:55]
	v_mfma_f32_16x16x32_bf16 v[48:51], v[176:179], v[184:187], v[48:51]
	v_mfma_f32_16x16x32_bf16 v[36:39], v[162:165], v[192:195], v[36:39]
	v_mfma_f32_16x16x32_bf16 v[32:35], v[176:179], v[192:195], v[32:35]
	v_mfma_f32_16x16x32_bf16 v[20:23], v[162:165], v[200:203], v[20:23]
	v_mfma_f32_16x16x32_bf16 v[16:19], v[176:179], v[200:203], v[16:19]
	v_mfma_f32_16x16x32_bf16 v[4:7], v[162:165], v[208:211], v[4:7]
	v_mfma_f32_16x16x32_bf16 v[0:3], v[176:179], v[208:211], v[0:3]
	s_barrier
	s_add_u32 s36, s36, 0x100
	s_addc_u32 s37, s37, 0
	s_cmp_ge_i32 s38, s87
	s_mov_b64 s[44:45], s[46:47]
	s_mov_b32 s30, s38
	s_cbranch_scc0 .LBB0_401
	s_and_b64 vcc, exec, s[12:13]
	s_cbranch_vccz .LBB0_404

.LBB0_1299:
	ds_read_b128 v[144:147], v153 offset:0
	ds_read_b128 v[156:159], v153 offset:1024
	ds_read_b128 v[160:163], v153 offset:2048
	ds_read_b128 v[164:167], v153 offset:3072
	ds_read_b128 v[168:171], v154 offset:0
	ds_read_b128 v[172:175], v154 offset:1024
	ds_read_b128 v[176:179], v154 offset:2048
	ds_read_b128 v[180:183], v154 offset:3072
	ds_read_b128 v[184:187], v155 offset:0
	ds_read_b128 v[188:191], v155 offset:1024
	ds_read_b128 v[192:195], v155 offset:2048
	ds_read_b128 v[196:199], v155 offset:3072
	ds_read_b128 v[202:205], v155 offset:4096
	ds_read_b128 v[206:209], v155 offset:5120
	ds_read_b128 v[210:213], v155 offset:6144
	ds_read_b128 v[214:217], v155 offset:7168
	s_add_u32 s36, s34, 0xfff00080
	s_addc_u32 s37, s35, -1
	s_cmp_eq_u32 s57, 60
	s_cselect_b32 s39, s13, s37
	s_cselect_b32 s38, s53, s36
	s_cselect_b32 s37, s11, s56
	s_cselect_b32 s36, s54, s55
	s_add_i32 m0, s31, 0xc000
	s_nop 0
	global_load_lds_dwordx4 v136, s[34:35]
	s_add_i32 m0, s31, 0xe000
	s_nop 0
	global_load_lds_dwordx4 v138, s[34:35]
	s_waitcnt vmcnt(8)
	s_waitcnt lgkmcnt(0)
	s_barrier
	v_mfma_f32_16x16x32_bf16 v[124:127], v[144:147], v[184:187], v[124:127]
	v_mfma_f32_16x16x32_bf16 v[120:123], v[160:163], v[184:187], v[120:123]
	v_mfma_f32_16x16x32_bf16 v[108:111], v[144:147], v[192:195], v[108:111]
	v_mfma_f32_16x16x32_bf16 v[104:107], v[160:163], v[192:195], v[104:107]
	v_mfma_f32_16x16x32_bf16 v[92:95], v[144:147], v[202:205], v[92:95]
	v_mfma_f32_16x16x32_bf16 v[88:91], v[160:163], v[202:205], v[88:91]
	v_mfma_f32_16x16x32_bf16 v[76:79], v[144:147], v[210:213], v[76:79]
	v_mfma_f32_16x16x32_bf16 v[72:75], v[160:163], v[210:213], v[72:75]
	v_mfma_f32_16x16x32_bf16 v[124:127], v[156:159], v[188:191], v[124:127]
	v_mfma_f32_16x16x32_bf16 v[120:123], v[164:167], v[188:191], v[120:123]
	v_mfma_f32_16x16x32_bf16 v[108:111], v[156:159], v[196:199], v[108:111]
	v_mfma_f32_16x16x32_bf16 v[104:107], v[164:167], v[196:199], v[104:107]
	v_mfma_f32_16x16x32_bf16 v[92:95], v[156:159], v[206:209], v[92:95]
	v_mfma_f32_16x16x32_bf16 v[88:91], v[164:167], v[206:209], v[88:91]
	v_mfma_f32_16x16x32_bf16 v[76:79], v[156:159], v[214:217], v[76:79]
	v_mfma_f32_16x16x32_bf16 v[72:75], v[164:167], v[214:217], v[72:75]
	v_mfma_f32_16x16x32_bf16 v[116:119], v[168:171], v[184:187], v[116:119]
	v_mfma_f32_16x16x32_bf16 v[112:115], v[176:179], v[184:187], v[112:115]
	v_mfma_f32_16x16x32_bf16 v[100:103], v[168:171], v[192:195], v[100:103]
	v_mfma_f32_16x16x32_bf16 v[96:99], v[176:179], v[192:195], v[96:99]
	v_mfma_f32_16x16x32_bf16 v[84:87], v[168:171], v[202:205], v[84:87]
	v_mfma_f32_16x16x32_bf16 v[80:83], v[176:179], v[202:205], v[80:83]
	v_mfma_f32_16x16x32_bf16 v[68:71], v[168:171], v[210:213], v[68:71]
	v_mfma_f32_16x16x32_bf16 v[64:67], v[176:179], v[210:213], v[64:67]
	v_mfma_f32_16x16x32_bf16 v[116:119], v[172:175], v[188:191], v[116:119]
	v_mfma_f32_16x16x32_bf16 v[112:115], v[180:183], v[188:191], v[112:115]
	v_mfma_f32_16x16x32_bf16 v[100:103], v[172:175], v[196:199], v[100:103]
	v_mfma_f32_16x16x32_bf16 v[96:99], v[180:183], v[196:199], v[96:99]
	v_mfma_f32_16x16x32_bf16 v[84:87], v[172:175], v[206:209], v[84:87]
	v_mfma_f32_16x16x32_bf16 v[80:83], v[180:183], v[206:209], v[80:83]
	v_mfma_f32_16x16x32_bf16 v[68:71], v[172:175], v[214:217], v[68:71]
	v_mfma_f32_16x16x32_bf16 v[64:67], v[180:183], v[214:217], v[64:67]
	s_barrier
	ds_read_b128 v[184:187], v155 offset:16384
	ds_read_b128 v[188:191], v155 offset:17408
	ds_read_b128 v[192:195], v155 offset:18432
	ds_read_b128 v[196:199], v155 offset:19456
	ds_read_b128 v[202:205], v155 offset:20480
	ds_read_b128 v[206:209], v155 offset:21504
	ds_read_b128 v[210:213], v155 offset:22528
	ds_read_b128 v[214:217], v155 offset:23552
	s_add_u32 s58, s36, 0x100000
	s_addc_u32 s59, s37, 0
	s_add_i32 m0, s31, 0x10000
	s_nop 0
	global_load_lds_dwordx4 v130, s[36:37]
	s_add_i32 m0, s31, 0x12000
	s_nop 0
	global_load_lds_dwordx4 v134, s[36:37]
	s_add_i32 m0, s31, 0x14000
	s_nop 0
	global_load_lds_dwordx4 v130, s[58:59]
	s_add_i32 m0, s31, 0x16000
	s_nop 0
	global_load_lds_dwordx4 v134, s[58:59]
	s_add_i32 m0, s31, 0x0
	s_nop 0
	global_load_lds_dwordx4 v128, s[38:39]
	s_add_i32 m0, s31, 0x2000
	s_nop 0
	global_load_lds_dwordx4 v132, s[38:39]
	s_waitcnt vmcnt(8)
	s_waitcnt lgkmcnt(0)
	s_barrier
	v_mfma_f32_16x16x32_bf16 v[60:63], v[144:147], v[184:187], v[60:63]
	v_mfma_f32_16x16x32_bf16 v[56:59], v[160:163], v[184:187], v[56:59]
	v_mfma_f32_16x16x32_bf16 v[44:47], v[144:147], v[192:195], v[44:47]
	v_mfma_f32_16x16x32_bf16 v[40:43], v[160:163], v[192:195], v[40:43]
	v_mfma_f32_16x16x32_bf16 v[28:31], v[144:147], v[202:205], v[28:31]
	v_mfma_f32_16x16x32_bf16 v[24:27], v[160:163], v[202:205], v[24:27]
	v_mfma_f32_16x16x32_bf16 v[12:15], v[144:147], v[210:213], v[12:15]
	v_mfma_f32_16x16x32_bf16 v[8:11], v[160:163], v[210:213], v[8:11]
	v_mfma_f32_16x16x32_bf16 v[60:63], v[156:159], v[188:191], v[60:63]
	v_mfma_f32_16x16x32_bf16 v[56:59], v[164:167], v[188:191], v[56:59]
	v_mfma_f32_16x16x32_bf16 v[44:47], v[156:159], v[196:199], v[44:47]
	v_mfma_f32_16x16x32_bf16 v[40:43], v[164:167], v[196:199], v[40:43]
	v_mfma_f32_16x16x32_bf16 v[28:31], v[156:159], v[206:209], v[28:31]
	v_mfma_f32_16x16x32_bf16 v[24:27], v[164:167], v[206:209], v[24:27]
	v_mfma_f32_16x16x32_bf16 v[12:15], v[156:159], v[214:217], v[12:15]
	v_mfma_f32_16x16x32_bf16 v[8:11], v[164:167], v[214:217], v[8:11]
	v_mfma_f32_16x16x32_bf16 v[52:55], v[168:171], v[184:187], v[52:55]
	v_mfma_f32_16x16x32_bf16 v[48:51], v[176:179], v[184:187], v[48:51]
	v_mfma_f32_16x16x32_bf16 v[36:39], v[168:171], v[192:195], v[36:39]
	v_mfma_f32_16x16x32_bf16 v[32:35], v[176:179], v[192:195], v[32:35]
	v_mfma_f32_16x16x32_bf16 v[20:23], v[168:171], v[202:205], v[20:23]
	v_mfma_f32_16x16x32_bf16 v[16:19], v[176:179], v[202:205], v[16:19]
	v_mfma_f32_16x16x32_bf16 v[4:7], v[168:171], v[210:213], v[4:7]
	v_mfma_f32_16x16x32_bf16 v[0:3], v[176:179], v[210:213], v[0:3]
	v_mfma_f32_16x16x32_bf16 v[52:55], v[172:175], v[188:191], v[52:55]
	v_mfma_f32_16x16x32_bf16 v[48:51], v[180:183], v[188:191], v[48:51]
	v_mfma_f32_16x16x32_bf16 v[36:39], v[172:175], v[196:199], v[36:39]
	v_mfma_f32_16x16x32_bf16 v[32:35], v[180:183], v[196:199], v[32:35]
	v_mfma_f32_16x16x32_bf16 v[20:23], v[172:175], v[206:209], v[20:23]
	v_mfma_f32_16x16x32_bf16 v[16:19], v[180:183], v[206:209], v[16:19]
	v_mfma_f32_16x16x32_bf16 v[4:7], v[172:175], v[214:217], v[4:7]
	v_mfma_f32_16x16x32_bf16 v[0:3], v[180:183], v[214:217], v[0:3]
	s_barrier
	ds_read_b128 v[144:147], v153 offset:32768
	ds_read_b128 v[156:159], v153 offset:33792
	ds_read_b128 v[160:163], v153 offset:34816
	ds_read_b128 v[164:167], v153 offset:35840
	ds_read_b128 v[168:171], v154 offset:32768
	ds_read_b128 v[172:175], v154 offset:33792
	ds_read_b128 v[176:179], v154 offset:34816
	ds_read_b128 v[180:183], v154 offset:35840
	ds_read_b128 v[184:187], v155 offset:32768
	ds_read_b128 v[188:191], v155 offset:33792
	ds_read_b128 v[192:195], v155 offset:34816
	ds_read_b128 v[196:199], v155 offset:35840
	ds_read_b128 v[202:205], v155 offset:36864
	ds_read_b128 v[206:209], v155 offset:37888
	ds_read_b128 v[210:213], v155 offset:38912
	ds_read_b128 v[214:217], v155 offset:39936
	s_add_u32 s98, s38, 0x100000
	s_addc_u32 s99, s39, 0
	s_add_i32 m0, s31, 0x4000
	s_nop 0
	global_load_lds_dwordx4 v128, s[98:99]
	s_add_i32 m0, s31, 0x6000
	s_nop 0
	global_load_lds_dwordx4 v132, s[98:99]
	s_waitcnt vmcnt(8)
	s_waitcnt lgkmcnt(0)
	s_barrier
	v_mfma_f32_16x16x32_bf16 v[124:127], v[144:147], v[184:187], v[124:127]
	v_mfma_f32_16x16x32_bf16 v[120:123], v[160:163], v[184:187], v[120:123]
	v_mfma_f32_16x16x32_bf16 v[108:111], v[144:147], v[192:195], v[108:111]
	v_mfma_f32_16x16x32_bf16 v[104:107], v[160:163], v[192:195], v[104:107]
	v_mfma_f32_16x16x32_bf16 v[92:95], v[144:147], v[202:205], v[92:95]
	v_mfma_f32_16x16x32_bf16 v[88:91], v[160:163], v[202:205], v[88:91]
	v_mfma_f32_16x16x32_bf16 v[76:79], v[144:147], v[210:213], v[76:79]
	v_mfma_f32_16x16x32_bf16 v[72:75], v[160:163], v[210:213], v[72:75]
	v_mfma_f32_16x16x32_bf16 v[124:127], v[156:159], v[188:191], v[124:127]
	v_mfma_f32_16x16x32_bf16 v[120:123], v[164:167], v[188:191], v[120:123]
	v_mfma_f32_16x16x32_bf16 v[108:111], v[156:159], v[196:199], v[108:111]
	v_mfma_f32_16x16x32_bf16 v[104:107], v[164:167], v[196:199], v[104:107]
	v_mfma_f32_16x16x32_bf16 v[92:95], v[156:159], v[206:209], v[92:95]
	v_mfma_f32_16x16x32_bf16 v[88:91], v[164:167], v[206:209], v[88:91]
	v_mfma_f32_16x16x32_bf16 v[76:79], v[156:159], v[214:217], v[76:79]
	v_mfma_f32_16x16x32_bf16 v[72:75], v[164:167], v[214:217], v[72:75]
	v_mfma_f32_16x16x32_bf16 v[116:119], v[168:171], v[184:187], v[116:119]
	v_mfma_f32_16x16x32_bf16 v[112:115], v[176:179], v[184:187], v[112:115]
	v_mfma_f32_16x16x32_bf16 v[100:103], v[168:171], v[192:195], v[100:103]
	v_mfma_f32_16x16x32_bf16 v[96:99], v[176:179], v[192:195], v[96:99]
	v_mfma_f32_16x16x32_bf16 v[84:87], v[168:171], v[202:205], v[84:87]
	v_mfma_f32_16x16x32_bf16 v[80:83], v[176:179], v[202:205], v[80:83]
	v_mfma_f32_16x16x32_bf16 v[68:71], v[168:171], v[210:213], v[68:71]
	v_mfma_f32_16x16x32_bf16 v[64:67], v[176:179], v[210:213], v[64:67]
	v_mfma_f32_16x16x32_bf16 v[116:119], v[172:175], v[188:191], v[116:119]
	v_mfma_f32_16x16x32_bf16 v[112:115], v[180:183], v[188:191], v[112:115]
	v_mfma_f32_16x16x32_bf16 v[100:103], v[172:175], v[196:199], v[100:103]
	v_mfma_f32_16x16x32_bf16 v[96:99], v[180:183], v[196:199], v[96:99]
	v_mfma_f32_16x16x32_bf16 v[84:87], v[172:175], v[206:209], v[84:87]
	v_mfma_f32_16x16x32_bf16 v[80:83], v[180:183], v[206:209], v[80:83]
	v_mfma_f32_16x16x32_bf16 v[68:71], v[172:175], v[214:217], v[68:71]
	v_mfma_f32_16x16x32_bf16 v[64:67], v[180:183], v[214:217], v[64:67]
	s_barrier
	ds_read_b128 v[184:187], v155 offset:49152
	ds_read_b128 v[188:191], v155 offset:50176
	ds_read_b128 v[192:195], v155 offset:51200
	ds_read_b128 v[196:199], v155 offset:52224
	ds_read_b128 v[202:205], v155 offset:53248
	ds_read_b128 v[206:209], v155 offset:54272
	ds_read_b128 v[210:213], v155 offset:55296
	ds_read_b128 v[214:217], v155 offset:56320
	s_add_u32 s100, s36, 0x80
	s_addc_u32 s101, s37, 0
	s_add_u32 s58, s36, 0x100080
	s_addc_u32 s59, s37, 0
	s_add_u32 s98, s38, 0x80
	s_addc_u32 s99, s39, 0
	s_add_i32 m0, s31, 0x18000
	s_nop 0
	global_load_lds_dwordx4 v130, s[100:101]
	s_add_i32 m0, s31, 0x1a000
	s_nop 0
	global_load_lds_dwordx4 v134, s[100:101]
	s_add_i32 m0, s31, 0x1c000
	s_nop 0
	global_load_lds_dwordx4 v130, s[58:59]
	s_add_i32 m0, s31, 0x1e000
	s_nop 0
	global_load_lds_dwordx4 v134, s[58:59]
	s_add_i32 m0, s31, 0x8000
	s_nop 0
	global_load_lds_dwordx4 v128, s[98:99]
	s_add_i32 m0, s31, 0xa000
	s_nop 0
	global_load_lds_dwordx4 v132, s[98:99]
	s_waitcnt vmcnt(8)
	s_waitcnt lgkmcnt(0)
	s_barrier
	v_mfma_f32_16x16x32_bf16 v[60:63], v[144:147], v[184:187], v[60:63]
	v_mfma_f32_16x16x32_bf16 v[56:59], v[160:163], v[184:187], v[56:59]
	v_mfma_f32_16x16x32_bf16 v[44:47], v[144:147], v[192:195], v[44:47]
	v_mfma_f32_16x16x32_bf16 v[40:43], v[160:163], v[192:195], v[40:43]
	v_mfma_f32_16x16x32_bf16 v[28:31], v[144:147], v[202:205], v[28:31]
	v_mfma_f32_16x16x32_bf16 v[24:27], v[160:163], v[202:205], v[24:27]
	v_mfma_f32_16x16x32_bf16 v[12:15], v[144:147], v[210:213], v[12:15]
	v_mfma_f32_16x16x32_bf16 v[8:11], v[160:163], v[210:213], v[8:11]
	v_mfma_f32_16x16x32_bf16 v[60:63], v[156:159], v[188:191], v[60:63]
	v_mfma_f32_16x16x32_bf16 v[56:59], v[164:167], v[188:191], v[56:59]
	v_mfma_f32_16x16x32_bf16 v[44:47], v[156:159], v[196:199], v[44:47]
	v_mfma_f32_16x16x32_bf16 v[40:43], v[164:167], v[196:199], v[40:43]
	v_mfma_f32_16x16x32_bf16 v[28:31], v[156:159], v[206:209], v[28:31]
	v_mfma_f32_16x16x32_bf16 v[24:27], v[164:167], v[206:209], v[24:27]
	v_mfma_f32_16x16x32_bf16 v[12:15], v[156:159], v[214:217], v[12:15]
	v_mfma_f32_16x16x32_bf16 v[8:11], v[164:167], v[214:217], v[8:11]
	v_mfma_f32_16x16x32_bf16 v[52:55], v[168:171], v[184:187], v[52:55]
	v_mfma_f32_16x16x32_bf16 v[48:51], v[176:179], v[184:187], v[48:51]
	v_mfma_f32_16x16x32_bf16 v[36:39], v[168:171], v[192:195], v[36:39]
	v_mfma_f32_16x16x32_bf16 v[32:35], v[176:179], v[192:195], v[32:35]
	v_mfma_f32_16x16x32_bf16 v[20:23], v[168:171], v[202:205], v[20:23]
	v_mfma_f32_16x16x32_bf16 v[16:19], v[176:179], v[202:205], v[16:19]
	v_mfma_f32_16x16x32_bf16 v[4:7], v[168:171], v[210:213], v[4:7]
	v_mfma_f32_16x16x32_bf16 v[0:3], v[176:179], v[210:213], v[0:3]
	v_mfma_f32_16x16x32_bf16 v[52:55], v[172:175], v[188:191], v[52:55]
	v_mfma_f32_16x16x32_bf16 v[48:51], v[180:183], v[188:191], v[48:51]
	v_mfma_f32_16x16x32_bf16 v[36:39], v[172:175], v[196:199], v[36:39]
	v_mfma_f32_16x16x32_bf16 v[32:35], v[180:183], v[196:199], v[32:35]
	v_mfma_f32_16x16x32_bf16 v[20:23], v[172:175], v[206:209], v[20:23]
	v_mfma_f32_16x16x32_bf16 v[16:19], v[180:183], v[206:209], v[16:19]
	v_mfma_f32_16x16x32_bf16 v[4:7], v[172:175], v[214:217], v[4:7]
	v_mfma_f32_16x16x32_bf16 v[0:3], v[180:183], v[214:217], v[0:3]
	s_barrier
	s_add_i32 s57, s57, 2
	s_add_u32 s34, s34, 0x100
	s_addc_u32 s35, s35, 0
	s_add_u32 s55, s55, 0x100
	s_addc_u32 s56, s56, 0
	s_cmp_gt_u32 s57, 61
	s_cbranch_scc0 .LBB0_1299
	s_and_b64 vcc, exec, s[6:7]
	s_cbranch_vccz .LBB0_1302
	s_barrier

.LBB0_1409:
	ds_read_b128 v[128:131], v177 offset:0
	ds_read_b128 v[146:149], v177 offset:1024
	ds_read_b128 v[150:153], v177 offset:2048
	ds_read_b128 v[154:157], v177 offset:3072
	ds_read_b128 v[158:161], v178 offset:0
	ds_read_b128 v[162:165], v178 offset:1024
	ds_read_b128 v[166:169], v178 offset:2048
	ds_read_b128 v[170:173], v178 offset:3072
	ds_read_b128 v[180:183], v179 offset:0
	ds_read_b128 v[184:187], v179 offset:1024
	ds_read_b128 v[188:191], v179 offset:2048
	ds_read_b128 v[192:195], v179 offset:3072
	ds_read_b128 v[196:199], v179 offset:4096
	ds_read_b128 v[202:205], v179 offset:5120
	ds_read_b128 v[206:209], v179 offset:6144
	ds_read_b128 v[210:213], v179 offset:7168
	s_add_i32 s70, s46, 2
	s_add_u32 s44, s42, 0x100
	s_addc_u32 s45, s43, 0
	s_cmp_eq_u32 s37, s46
	s_cselect_b32 s46, s40, s68
	s_cselect_b32 s49, s39, s45
	s_cselect_b32 s48, s38, s44
	s_cselect_b32 s47, s41, s69
	s_add_i32 m0, s50, 0xc000
	s_nop 0
	global_load_lds_dwordx4 v140, s[42:43]
	s_add_i32 m0, s50, 0xe000
	s_nop 0
	global_load_lds_dwordx4 v142, s[42:43]
	s_waitcnt vmcnt(8)
	s_waitcnt lgkmcnt(0)
	s_barrier
	v_mfma_f32_16x16x32_bf16 v[124:127], v[128:131], v[180:183], v[124:127]
	v_mfma_f32_16x16x32_bf16 v[120:123], v[150:153], v[180:183], v[120:123]
	v_mfma_f32_16x16x32_bf16 v[108:111], v[128:131], v[188:191], v[108:111]
	v_mfma_f32_16x16x32_bf16 v[104:107], v[150:153], v[188:191], v[104:107]
	v_mfma_f32_16x16x32_bf16 v[92:95], v[128:131], v[196:199], v[92:95]
	v_mfma_f32_16x16x32_bf16 v[88:91], v[150:153], v[196:199], v[88:91]
	v_mfma_f32_16x16x32_bf16 v[76:79], v[128:131], v[206:209], v[76:79]
	v_mfma_f32_16x16x32_bf16 v[72:75], v[150:153], v[206:209], v[72:75]
	v_mfma_f32_16x16x32_bf16 v[124:127], v[146:149], v[184:187], v[124:127]
	v_mfma_f32_16x16x32_bf16 v[120:123], v[154:157], v[184:187], v[120:123]
	v_mfma_f32_16x16x32_bf16 v[108:111], v[146:149], v[192:195], v[108:111]
	v_mfma_f32_16x16x32_bf16 v[104:107], v[154:157], v[192:195], v[104:107]
	v_mfma_f32_16x16x32_bf16 v[92:95], v[146:149], v[202:205], v[92:95]
	v_mfma_f32_16x16x32_bf16 v[88:91], v[154:157], v[202:205], v[88:91]
	v_mfma_f32_16x16x32_bf16 v[76:79], v[146:149], v[210:213], v[76:79]
	v_mfma_f32_16x16x32_bf16 v[72:75], v[154:157], v[210:213], v[72:75]
	v_mfma_f32_16x16x32_bf16 v[116:119], v[158:161], v[180:183], v[116:119]
	v_mfma_f32_16x16x32_bf16 v[112:115], v[166:169], v[180:183], v[112:115]
	v_mfma_f32_16x16x32_bf16 v[100:103], v[158:161], v[188:191], v[100:103]
	v_mfma_f32_16x16x32_bf16 v[96:99], v[166:169], v[188:191], v[96:99]
	v_mfma_f32_16x16x32_bf16 v[84:87], v[158:161], v[196:199], v[84:87]
	v_mfma_f32_16x16x32_bf16 v[80:83], v[166:169], v[196:199], v[80:83]
	v_mfma_f32_16x16x32_bf16 v[68:71], v[158:161], v[206:209], v[68:71]
	v_mfma_f32_16x16x32_bf16 v[64:67], v[166:169], v[206:209], v[64:67]
	v_mfma_f32_16x16x32_bf16 v[116:119], v[162:165], v[184:187], v[116:119]
	v_mfma_f32_16x16x32_bf16 v[112:115], v[170:173], v[184:187], v[112:115]
	v_mfma_f32_16x16x32_bf16 v[100:103], v[162:165], v[192:195], v[100:103]
	v_mfma_f32_16x16x32_bf16 v[96:99], v[170:173], v[192:195], v[96:99]
	v_mfma_f32_16x16x32_bf16 v[84:87], v[162:165], v[202:205], v[84:87]
	v_mfma_f32_16x16x32_bf16 v[80:83], v[170:173], v[202:205], v[80:83]
	v_mfma_f32_16x16x32_bf16 v[68:71], v[162:165], v[210:213], v[68:71]
	v_mfma_f32_16x16x32_bf16 v[64:67], v[170:173], v[210:213], v[64:67]
	s_barrier
	ds_read_b128 v[180:183], v179 offset:16384
	ds_read_b128 v[184:187], v179 offset:17408
	ds_read_b128 v[188:191], v179 offset:18432
	ds_read_b128 v[192:195], v179 offset:19456
	ds_read_b128 v[196:199], v179 offset:20480
	ds_read_b128 v[202:205], v179 offset:21504
	ds_read_b128 v[206:209], v179 offset:22528
	ds_read_b128 v[210:213], v179 offset:23552
	s_add_u32 s42, s46, 0x2b0000
	s_addc_u32 s43, s47, 0
	s_add_i32 m0, s50, 0x10000
	s_nop 0
	global_load_lds_dwordx4 v134, s[46:47]
	s_add_i32 m0, s50, 0x12000
	s_nop 0
	global_load_lds_dwordx4 v138, s[46:47]
	s_add_i32 m0, s50, 0x14000
	s_nop 0
	global_load_lds_dwordx4 v134, s[42:43]
	s_add_i32 m0, s50, 0x16000
	s_nop 0
	global_load_lds_dwordx4 v138, s[42:43]
	s_add_i32 m0, s50, 0x0
	s_nop 0
	global_load_lds_dwordx4 v132, s[48:49]
	s_add_i32 m0, s50, 0x2000
	s_nop 0
	global_load_lds_dwordx4 v136, s[48:49]
	s_waitcnt vmcnt(8)
	s_waitcnt lgkmcnt(0)
	s_barrier
	v_mfma_f32_16x16x32_bf16 v[60:63], v[128:131], v[180:183], v[60:63]
	v_mfma_f32_16x16x32_bf16 v[56:59], v[150:153], v[180:183], v[56:59]
	v_mfma_f32_16x16x32_bf16 v[44:47], v[128:131], v[188:191], v[44:47]
	v_mfma_f32_16x16x32_bf16 v[40:43], v[150:153], v[188:191], v[40:43]
	v_mfma_f32_16x16x32_bf16 v[28:31], v[128:131], v[196:199], v[28:31]
	v_mfma_f32_16x16x32_bf16 v[24:27], v[150:153], v[196:199], v[24:27]
	v_mfma_f32_16x16x32_bf16 v[12:15], v[128:131], v[206:209], v[12:15]
	v_mfma_f32_16x16x32_bf16 v[8:11], v[150:153], v[206:209], v[8:11]
	v_mfma_f32_16x16x32_bf16 v[60:63], v[146:149], v[184:187], v[60:63]
	v_mfma_f32_16x16x32_bf16 v[56:59], v[154:157], v[184:187], v[56:59]
	v_mfma_f32_16x16x32_bf16 v[44:47], v[146:149], v[192:195], v[44:47]
	v_mfma_f32_16x16x32_bf16 v[40:43], v[154:157], v[192:195], v[40:43]
	v_mfma_f32_16x16x32_bf16 v[28:31], v[146:149], v[202:205], v[28:31]
	v_mfma_f32_16x16x32_bf16 v[24:27], v[154:157], v[202:205], v[24:27]
	v_mfma_f32_16x16x32_bf16 v[12:15], v[146:149], v[210:213], v[12:15]
	v_mfma_f32_16x16x32_bf16 v[8:11], v[154:157], v[210:213], v[8:11]
	v_mfma_f32_16x16x32_bf16 v[52:55], v[158:161], v[180:183], v[52:55]
	v_mfma_f32_16x16x32_bf16 v[48:51], v[166:169], v[180:183], v[48:51]
	v_mfma_f32_16x16x32_bf16 v[36:39], v[158:161], v[188:191], v[36:39]
	v_mfma_f32_16x16x32_bf16 v[32:35], v[166:169], v[188:191], v[32:35]
	v_mfma_f32_16x16x32_bf16 v[20:23], v[158:161], v[196:199], v[20:23]
	v_mfma_f32_16x16x32_bf16 v[16:19], v[166:169], v[196:199], v[16:19]
	v_mfma_f32_16x16x32_bf16 v[4:7], v[158:161], v[206:209], v[4:7]
	v_mfma_f32_16x16x32_bf16 v[0:3], v[166:169], v[206:209], v[0:3]
	v_mfma_f32_16x16x32_bf16 v[52:55], v[162:165], v[184:187], v[52:55]
	v_mfma_f32_16x16x32_bf16 v[48:51], v[170:173], v[184:187], v[48:51]
	v_mfma_f32_16x16x32_bf16 v[36:39], v[162:165], v[192:195], v[36:39]
	v_mfma_f32_16x16x32_bf16 v[32:35], v[170:173], v[192:195], v[32:35]
	v_mfma_f32_16x16x32_bf16 v[20:23], v[162:165], v[202:205], v[20:23]
	v_mfma_f32_16x16x32_bf16 v[16:19], v[170:173], v[202:205], v[16:19]
	v_mfma_f32_16x16x32_bf16 v[4:7], v[162:165], v[210:213], v[4:7]
	v_mfma_f32_16x16x32_bf16 v[0:3], v[170:173], v[210:213], v[0:3]
	s_barrier
	ds_read_b128 v[128:131], v177 offset:32768
	ds_read_b128 v[146:149], v177 offset:33792
	ds_read_b128 v[150:153], v177 offset:34816
	ds_read_b128 v[154:157], v177 offset:35840
	ds_read_b128 v[158:161], v178 offset:32768
	ds_read_b128 v[162:165], v178 offset:33792
	ds_read_b128 v[166:169], v178 offset:34816
	ds_read_b128 v[170:173], v178 offset:35840
	ds_read_b128 v[180:183], v179 offset:32768
	ds_read_b128 v[184:187], v179 offset:33792
	ds_read_b128 v[188:191], v179 offset:34816
	ds_read_b128 v[192:195], v179 offset:35840
	ds_read_b128 v[196:199], v179 offset:36864
	ds_read_b128 v[202:205], v179 offset:37888
	ds_read_b128 v[206:209], v179 offset:38912
	ds_read_b128 v[210:213], v179 offset:39936
	s_add_u32 s98, s48, 0x2b0000
	s_addc_u32 s99, s49, 0
	s_add_i32 m0, s50, 0x4000
	s_nop 0
	global_load_lds_dwordx4 v132, s[98:99]
	s_add_i32 m0, s50, 0x6000
	s_nop 0
	global_load_lds_dwordx4 v136, s[98:99]
	s_waitcnt vmcnt(8)
	s_waitcnt lgkmcnt(0)
	s_barrier
	v_mfma_f32_16x16x32_bf16 v[124:127], v[128:131], v[180:183], v[124:127]
	v_mfma_f32_16x16x32_bf16 v[120:123], v[150:153], v[180:183], v[120:123]
	v_mfma_f32_16x16x32_bf16 v[108:111], v[128:131], v[188:191], v[108:111]
	v_mfma_f32_16x16x32_bf16 v[104:107], v[150:153], v[188:191], v[104:107]
	v_mfma_f32_16x16x32_bf16 v[92:95], v[128:131], v[196:199], v[92:95]
	v_mfma_f32_16x16x32_bf16 v[88:91], v[150:153], v[196:199], v[88:91]
	v_mfma_f32_16x16x32_bf16 v[76:79], v[128:131], v[206:209], v[76:79]
	v_mfma_f32_16x16x32_bf16 v[72:75], v[150:153], v[206:209], v[72:75]
	v_mfma_f32_16x16x32_bf16 v[124:127], v[146:149], v[184:187], v[124:127]
	v_mfma_f32_16x16x32_bf16 v[120:123], v[154:157], v[184:187], v[120:123]
	v_mfma_f32_16x16x32_bf16 v[108:111], v[146:149], v[192:195], v[108:111]
	v_mfma_f32_16x16x32_bf16 v[104:107], v[154:157], v[192:195], v[104:107]
	v_mfma_f32_16x16x32_bf16 v[92:95], v[146:149], v[202:205], v[92:95]
	v_mfma_f32_16x16x32_bf16 v[88:91], v[154:157], v[202:205], v[88:91]
	v_mfma_f32_16x16x32_bf16 v[76:79], v[146:149], v[210:213], v[76:79]
	v_mfma_f32_16x16x32_bf16 v[72:75], v[154:157], v[210:213], v[72:75]
	v_mfma_f32_16x16x32_bf16 v[116:119], v[158:161], v[180:183], v[116:119]
	v_mfma_f32_16x16x32_bf16 v[112:115], v[166:169], v[180:183], v[112:115]
	v_mfma_f32_16x16x32_bf16 v[100:103], v[158:161], v[188:191], v[100:103]
	v_mfma_f32_16x16x32_bf16 v[96:99], v[166:169], v[188:191], v[96:99]
	v_mfma_f32_16x16x32_bf16 v[84:87], v[158:161], v[196:199], v[84:87]
	v_mfma_f32_16x16x32_bf16 v[80:83], v[166:169], v[196:199], v[80:83]
	v_mfma_f32_16x16x32_bf16 v[68:71], v[158:161], v[206:209], v[68:71]
	v_mfma_f32_16x16x32_bf16 v[64:67], v[166:169], v[206:209], v[64:67]
	v_mfma_f32_16x16x32_bf16 v[116:119], v[162:165], v[184:187], v[116:119]
	v_mfma_f32_16x16x32_bf16 v[112:115], v[170:173], v[184:187], v[112:115]
	v_mfma_f32_16x16x32_bf16 v[100:103], v[162:165], v[192:195], v[100:103]
	v_mfma_f32_16x16x32_bf16 v[96:99], v[170:173], v[192:195], v[96:99]
	v_mfma_f32_16x16x32_bf16 v[84:87], v[162:165], v[202:205], v[84:87]
	v_mfma_f32_16x16x32_bf16 v[80:83], v[170:173], v[202:205], v[80:83]
	v_mfma_f32_16x16x32_bf16 v[68:71], v[162:165], v[210:213], v[68:71]
	v_mfma_f32_16x16x32_bf16 v[64:67], v[170:173], v[210:213], v[64:67]
	s_barrier
	ds_read_b128 v[180:183], v179 offset:49152
	ds_read_b128 v[184:187], v179 offset:50176
	ds_read_b128 v[188:191], v179 offset:51200
	ds_read_b128 v[192:195], v179 offset:52224
	ds_read_b128 v[196:199], v179 offset:53248
	ds_read_b128 v[202:205], v179 offset:54272
	ds_read_b128 v[206:209], v179 offset:55296
	ds_read_b128 v[210:213], v179 offset:56320
	s_add_u32 s100, s46, 0x80
	s_addc_u32 s101, s47, 0
	s_add_u32 s42, s46, 0x2b0080
	s_addc_u32 s43, s47, 0
	s_add_u32 s98, s48, 0x80
	s_addc_u32 s99, s49, 0
	s_add_i32 m0, s50, 0x18000
	s_nop 0
	global_load_lds_dwordx4 v134, s[100:101]
	s_add_i32 m0, s50, 0x1a000
	s_nop 0
	global_load_lds_dwordx4 v138, s[100:101]
	s_add_i32 m0, s50, 0x1c000
	s_nop 0
	global_load_lds_dwordx4 v134, s[42:43]
	s_add_i32 m0, s50, 0x1e000
	s_nop 0
	global_load_lds_dwordx4 v138, s[42:43]
	s_add_i32 m0, s50, 0x8000
	s_nop 0
	global_load_lds_dwordx4 v132, s[98:99]
	s_add_i32 m0, s50, 0xa000
	s_nop 0
	global_load_lds_dwordx4 v136, s[98:99]
	s_waitcnt vmcnt(8)
	s_waitcnt lgkmcnt(0)
	s_barrier
	v_mfma_f32_16x16x32_bf16 v[60:63], v[128:131], v[180:183], v[60:63]
	v_mfma_f32_16x16x32_bf16 v[56:59], v[150:153], v[180:183], v[56:59]
	v_mfma_f32_16x16x32_bf16 v[44:47], v[128:131], v[188:191], v[44:47]
	v_mfma_f32_16x16x32_bf16 v[40:43], v[150:153], v[188:191], v[40:43]
	v_mfma_f32_16x16x32_bf16 v[28:31], v[128:131], v[196:199], v[28:31]
	v_mfma_f32_16x16x32_bf16 v[24:27], v[150:153], v[196:199], v[24:27]
	v_mfma_f32_16x16x32_bf16 v[12:15], v[128:131], v[206:209], v[12:15]
	v_mfma_f32_16x16x32_bf16 v[8:11], v[150:153], v[206:209], v[8:11]
	v_mfma_f32_16x16x32_bf16 v[60:63], v[146:149], v[184:187], v[60:63]
	v_mfma_f32_16x16x32_bf16 v[56:59], v[154:157], v[184:187], v[56:59]
	v_mfma_f32_16x16x32_bf16 v[44:47], v[146:149], v[192:195], v[44:47]
	v_mfma_f32_16x16x32_bf16 v[40:43], v[154:157], v[192:195], v[40:43]
	v_mfma_f32_16x16x32_bf16 v[28:31], v[146:149], v[202:205], v[28:31]
	v_mfma_f32_16x16x32_bf16 v[24:27], v[154:157], v[202:205], v[24:27]
	v_mfma_f32_16x16x32_bf16 v[12:15], v[146:149], v[210:213], v[12:15]
	v_mfma_f32_16x16x32_bf16 v[8:11], v[154:157], v[210:213], v[8:11]
	v_mfma_f32_16x16x32_bf16 v[52:55], v[158:161], v[180:183], v[52:55]
	v_mfma_f32_16x16x32_bf16 v[48:51], v[166:169], v[180:183], v[48:51]
	v_mfma_f32_16x16x32_bf16 v[36:39], v[158:161], v[188:191], v[36:39]
	v_mfma_f32_16x16x32_bf16 v[32:35], v[166:169], v[188:191], v[32:35]
	v_mfma_f32_16x16x32_bf16 v[20:23], v[158:161], v[196:199], v[20:23]
	v_mfma_f32_16x16x32_bf16 v[16:19], v[166:169], v[196:199], v[16:19]
	v_mfma_f32_16x16x32_bf16 v[4:7], v[158:161], v[206:209], v[4:7]
	v_mfma_f32_16x16x32_bf16 v[0:3], v[166:169], v[206:209], v[0:3]
	v_mfma_f32_16x16x32_bf16 v[52:55], v[162:165], v[184:187], v[52:55]
	v_mfma_f32_16x16x32_bf16 v[48:51], v[170:173], v[184:187], v[48:51]
	v_mfma_f32_16x16x32_bf16 v[36:39], v[162:165], v[192:195], v[36:39]
	v_mfma_f32_16x16x32_bf16 v[32:35], v[170:173], v[192:195], v[32:35]
	v_mfma_f32_16x16x32_bf16 v[20:23], v[162:165], v[202:205], v[20:23]
	v_mfma_f32_16x16x32_bf16 v[16:19], v[170:173], v[202:205], v[16:19]
	v_mfma_f32_16x16x32_bf16 v[4:7], v[162:165], v[210:213], v[4:7]
	v_mfma_f32_16x16x32_bf16 v[0:3], v[170:173], v[210:213], v[0:3]
	s_barrier
	s_add_u32 s68, s68, 0x100
	s_addc_u32 s69, s69, 0
	s_cmp_ge_i32 s70, s67
	s_mov_b64 s[42:43], s[44:45]
	s_mov_b32 s46, s70
	s_cbranch_scc0 .LBB0_1409
	s_and_b64 vcc, exec, s[14:15]
	s_cbranch_vccz .LBB0_1412
